# sample_item<0> state streaming: 8 loads per trip hoisted with counted vmcnt; sample_item<1> streaming: vmcnt(0) replaced by counted waits
# baseline (speedup 1.0000x reference)
; #define LAS __attribute__((address_space(3)))
; template <int TY> __device__ __forceinline__ void sample_item(const Params& p, ldsp lds, int item) {
;     ...
; #pragma unroll 8
;     for (int d = dg; d < DK; d += NG) { const f32x4 s0 = __builtin_nontemporal_load((const f32x4*)(S0 + (size_t)d * DV + e4 * 4));
;         const f32x4 qa = *(const LAS f32x4*)(QK + d * 16), qb = *(const LAS f32x4*)(QK + d * 16 + 4), ka = *(const LAS f32x4*)(QK + d * 16 + 8), kb = *(const LAS f32x4*)(QK + d * 16 + 12);
;         const float dc = DECs[d];
;         o[0] += s0 * qa[0]; o[1] += s0 * qa[1]; o[2] += s0 * qa[2]; o[3] += s0 * qa[3]; o[4] += s0 * qb[0]; o[5] += s0 * qb[1]; o[6] += s0 * qb[2]; o[7] += s0 * qb[3];
;         f32x4 sn = s0 * dc; sn += v[0] * ka[0]; sn += v[1] * ka[1]; sn += v[2] * ka[2]; sn += v[3] * ka[3]; sn += v[4] * kb[0]; sn += v[5] * kb[1]; sn += v[6] * kb[2]; sn += v[7] * kb[3];
;         __builtin_nontemporal_store(sn, (f32x4*)(S1 + (size_t)d * DV + e4 * 4)); }
.LBB0_1005:
	v_lshl_add_u64 v[100:101], v[96:97], 0, s[8:9]
	global_load_dwordx4 v[186:189], v[100:101], off nt
	v_lshl_add_u64 v[190:191], v[94:95], 0, s[8:9]
	global_load_dwordx4 v[192:195], v[190:191], off nt
	v_lshl_add_u64 v[196:197], v[90:91], 0, s[8:9]
	global_load_dwordx4 v[198:201], v[196:197], off nt
	v_lshl_add_u64 v[202:203], v[86:87], 0, s[8:9]
	global_load_dwordx4 v[204:207], v[202:203], off nt
	v_lshl_add_u64 v[208:209], v[82:83], 0, s[8:9]
	global_load_dwordx4 v[210:213], v[208:209], off nt
	v_lshl_add_u64 v[214:215], v[78:79], 0, s[8:9]
	global_load_dwordx4 v[216:219], v[214:215], off nt
	v_lshl_add_u64 v[220:221], v[74:75], 0, s[8:9]
	global_load_dwordx4 v[222:225], v[220:221], off nt
	v_lshl_add_u64 v[226:227], v[70:71], 0, s[8:9]
	global_load_dwordx4 v[228:231], v[226:227], off nt
	ds_read_b128 v[108:111], v116
	ds_read_b128 v[118:121], v116 offset:16
	ds_read_b128 v[122:125], v116 offset:32
	ds_read_b128 v[126:129], v116 offset:48
	ds_read2_b32 v[100:101], v16 offset1:16
	s_waitcnt lgkmcnt(0)
	v_mov_b32_e32 v102, v111
	v_add_u32_e32 v69, 0x80, v69
	v_cmp_lt_i32_e32 vcc, -1, v69
	v_lshl_add_u64 v[96:97], v[96:97], 0, s[44:45]
	s_or_b64 s[16:17], vcc, s[16:17]
	s_waitcnt vmcnt(7)
	v_pk_fma_f32 v[64:65], v[186:187], v[108:109], v[64:65] op_sel_hi:[1,0,1]
	v_pk_fma_f32 v[66:67], v[188:189], v[108:109], v[66:67] op_sel_hi:[1,0,1]
	v_pk_fma_f32 v[60:61], v[186:187], v[108:109], v[60:61] op_sel:[0,1,0]
	v_pk_fma_f32 v[62:63], v[188:189], v[108:109], v[62:63] op_sel:[0,1,0]
	v_mov_b32_e32 v108, v121
	v_pk_fma_f32 v[56:57], v[186:187], v[110:111], v[56:57] op_sel_hi:[1,0,1]
	v_pk_fma_f32 v[52:53], v[186:187], v[102:103], v[52:53] op_sel_hi:[1,0,1]
	v_pk_fma_f32 v[54:55], v[188:189], v[102:103], v[54:55] op_sel_hi:[1,0,1]
	v_pk_fma_f32 v[48:49], v[186:187], v[118:119], v[48:49] op_sel_hi:[1,0,1]
	v_pk_fma_f32 v[40:41], v[186:187], v[118:119], v[40:41] op_sel:[0,1,0]
	v_pk_fma_f32 v[36:37], v[186:187], v[120:121], v[36:37] op_sel_hi:[1,0,1]
	v_pk_fma_f32 v[102:103], v[188:189], v[120:121], v[38:39] op_sel_hi:[1,0,1]
	v_pk_fma_f32 v[38:39], v[186:187], v[108:109], v[44:45] op_sel_hi:[1,0,1]
	v_pk_fma_f32 v[44:45], v[188:189], v[108:109], v[46:47] op_sel_hi:[1,0,1]
	v_pk_mul_f32 v[46:47], v[186:187], v[100:101] op_sel_hi:[1,0]
	v_pk_mul_f32 v[104:105], v[188:189], v[100:101] op_sel_hi:[1,0]
	v_pk_fma_f32 v[46:47], v[0:1], v[122:123], v[46:47] op_sel_hi:[1,0,1]
	v_pk_fma_f32 v[104:105], v[2:3], v[122:123], v[104:105] op_sel_hi:[1,0,1]
	v_pk_fma_f32 v[46:47], v[4:5], v[122:123], v[46:47] op_sel:[0,1,0]
	v_pk_fma_f32 v[104:105], v[6:7], v[122:123], v[104:105] op_sel:[0,1,0]
	v_pk_fma_f32 v[46:47], v[8:9], v[124:125], v[46:47] op_sel_hi:[1,0,1]
	v_pk_fma_f32 v[104:105], v[10:11], v[124:125], v[104:105] op_sel_hi:[1,0,1]
	v_mov_b32_e32 v100, v125
	v_pk_fma_f32 v[46:47], v[12:13], v[100:101], v[46:47] op_sel_hi:[1,0,1]
	v_pk_fma_f32 v[104:105], v[14:15], v[100:101], v[104:105] op_sel_hi:[1,0,1]
	v_pk_fma_f32 v[46:47], v[20:21], v[126:127], v[46:47] op_sel_hi:[1,0,1]
	v_pk_fma_f32 v[104:105], v[22:23], v[126:127], v[104:105] op_sel_hi:[1,0,1]
	v_pk_fma_f32 v[46:47], v[24:25], v[126:127], v[46:47] op_sel:[0,1,0]
	v_pk_fma_f32 v[104:105], v[26:27], v[126:127], v[104:105] op_sel:[0,1,0]
	v_pk_fma_f32 v[58:59], v[188:189], v[110:111], v[58:59] op_sel_hi:[1,0,1]
	v_pk_fma_f32 v[50:51], v[188:189], v[118:119], v[50:51] op_sel_hi:[1,0,1]
	v_pk_fma_f32 v[42:43], v[188:189], v[118:119], v[42:43] op_sel:[0,1,0]
	v_pk_fma_f32 v[106:107], v[30:31], v[128:129], v[104:105] op_sel_hi:[1,0,1]
	v_pk_fma_f32 v[46:47], v[28:29], v[128:129], v[46:47] op_sel_hi:[1,0,1]
	v_mov_b32_e32 v100, v129
	v_pk_fma_f32 v[104:105], v[32:33], v[100:101], v[46:47] op_sel_hi:[1,0,1]
	v_pk_fma_f32 v[106:107], v[34:35], v[100:101], v[106:107] op_sel_hi:[1,0,1]
	v_lshl_add_u64 v[46:47], v[98:99], 0, s[8:9]
	global_store_dwordx4 v[46:47], v[104:107], off nt
	v_lshl_add_u64 v[46:47], v[94:95], 0, s[8:9]
	ds_read_b128 v[108:111], v116 offset:1024
	ds_read_b128 v[118:121], v116 offset:1040
	ds_read_b128 v[122:125], v116 offset:1056
	ds_read_b128 v[126:129], v116 offset:1072
	v_lshl_add_u64 v[94:95], v[94:95], 0, s[44:45]
	s_waitcnt lgkmcnt(3)
	v_mov_b32_e32 v46, v111
	v_lshl_add_u64 v[98:99], v[98:99], 0, s[44:45]
	s_waitcnt lgkmcnt(2)
	s_waitcnt vmcnt(7)
	v_pk_fma_f32 v[134:135], v[192:193], v[120:121], v[36:37] op_sel_hi:[1,0,1]
	v_mov_b32_e32 v36, v121
	v_pk_fma_f32 v[102:103], v[194:195], v[120:121], v[102:103] op_sel_hi:[1,0,1]
	v_pk_fma_f32 v[120:121], v[194:195], v[36:37], v[44:45] op_sel_hi:[1,0,1]
	v_pk_fma_f32 v[136:137], v[192:193], v[36:37], v[38:39] op_sel_hi:[1,0,1]
	v_mov_b32_e32 v36, v101
	v_pk_mul_f32 v[38:39], v[192:193], v[36:37] op_sel_hi:[1,0]
	v_pk_mul_f32 v[36:37], v[194:195], v[36:37] op_sel_hi:[1,0]
	s_waitcnt lgkmcnt(1)
	v_pk_fma_f32 v[38:39], v[0:1], v[122:123], v[38:39] op_sel_hi:[1,0,1]
	v_pk_fma_f32 v[36:37], v[2:3], v[122:123], v[36:37] op_sel_hi:[1,0,1]
	v_pk_fma_f32 v[38:39], v[4:5], v[122:123], v[38:39] op_sel:[0,1,0]
	v_pk_fma_f32 v[36:37], v[6:7], v[122:123], v[36:37] op_sel:[0,1,0]
	v_pk_fma_f32 v[112:113], v[194:195], v[118:119], v[50:51] op_sel_hi:[1,0,1]
	v_pk_fma_f32 v[130:131], v[192:193], v[118:119], v[48:49] op_sel_hi:[1,0,1]
	v_pk_fma_f32 v[132:133], v[194:195], v[118:119], v[42:43] op_sel:[0,1,0]
	v_pk_fma_f32 v[118:119], v[192:193], v[118:119], v[40:41] op_sel:[0,1,0]
	v_pk_fma_f32 v[36:37], v[10:11], v[124:125], v[36:37] op_sel_hi:[1,0,1]
	v_pk_fma_f32 v[38:39], v[8:9], v[124:125], v[38:39] op_sel_hi:[1,0,1]
	v_mov_b32_e32 v40, v125
	v_pk_fma_f32 v[38:39], v[12:13], v[40:41], v[38:39] op_sel_hi:[1,0,1]
	v_pk_fma_f32 v[36:37], v[14:15], v[40:41], v[36:37] op_sel_hi:[1,0,1]
	s_waitcnt lgkmcnt(0)
; #define LAS __attribute__((address_space(3)))
; template <int TY> __device__ __forceinline__ void sample_item(const Params& p, ldsp lds, int item) {
;     ...
; #pragma unroll 8
;     for (int d = dg; d < DK; d += NG) { const f32x4 s0 = __builtin_nontemporal_load((const f32x4*)(S0 + (size_t)d * DV + e4 * 4));
;         const f32x4 qa = *(const LAS f32x4*)(QK + d * 16), qb = *(const LAS f32x4*)(QK + d * 16 + 4), ka = *(const LAS f32x4*)(QK + d * 16 + 8), kb = *(const LAS f32x4*)(QK + d * 16 + 12);
;         const float dc = DECs[d];
;         o[0] += s0 * qa[0]; o[1] += s0 * qa[1]; o[2] += s0 * qa[2]; o[3] += s0 * qa[3]; o[4] += s0 * qb[0]; o[5] += s0 * qb[1]; o[6] += s0 * qb[2]; o[7] += s0 * qb[3];
;         f32x4 sn = s0 * dc; sn += v[0] * ka[0]; sn += v[1] * ka[1]; sn += v[2] * ka[2]; sn += v[3] * ka[3]; sn += v[4] * kb[0]; sn += v[5] * kb[1]; sn += v[6] * kb[2]; sn += v[7] * kb[3];
;         __builtin_nontemporal_store(sn, (f32x4*)(S1 + (size_t)d * DV + e4 * 4)); }
	v_pk_fma_f32 v[38:39], v[20:21], v[126:127], v[38:39] op_sel_hi:[1,0,1]
	v_pk_fma_f32 v[36:37], v[22:23], v[126:127], v[36:37] op_sel_hi:[1,0,1]
	v_pk_fma_f32 v[38:39], v[24:25], v[126:127], v[38:39] op_sel:[0,1,0]
	v_pk_fma_f32 v[36:37], v[26:27], v[126:127], v[36:37] op_sel:[0,1,0]
	v_pk_fma_f32 v[66:67], v[194:195], v[108:109], v[66:67] op_sel_hi:[1,0,1]
	v_pk_fma_f32 v[40:41], v[30:31], v[128:129], v[36:37] op_sel_hi:[1,0,1]
	v_pk_fma_f32 v[36:37], v[28:29], v[128:129], v[38:39] op_sel_hi:[1,0,1]
	v_mov_b32_e32 v38, v129
	v_pk_fma_f32 v[36:37], v[32:33], v[38:39], v[36:37] op_sel_hi:[1,0,1]
	v_pk_fma_f32 v[38:39], v[34:35], v[38:39], v[40:41] op_sel_hi:[1,0,1]
	v_lshl_add_u64 v[40:41], v[92:93], 0, s[8:9]
	global_store_dwordx4 v[40:41], v[36:39], off nt
	v_pk_fma_f32 v[64:65], v[192:193], v[108:109], v[64:65] op_sel_hi:[1,0,1]
	v_pk_fma_f32 v[62:63], v[194:195], v[108:109], v[62:63] op_sel:[0,1,0]
	v_lshl_add_u64 v[36:37], v[90:91], 0, s[8:9]
	v_pk_fma_f32 v[60:61], v[192:193], v[108:109], v[60:61] op_sel:[0,1,0]
	v_pk_fma_f32 v[58:59], v[194:195], v[110:111], v[58:59] op_sel_hi:[1,0,1]
	v_pk_fma_f32 v[56:57], v[192:193], v[110:111], v[56:57] op_sel_hi:[1,0,1]
	v_pk_fma_f32 v[108:109], v[194:195], v[46:47], v[54:55] op_sel_hi:[1,0,1]
	v_pk_fma_f32 v[110:111], v[192:193], v[46:47], v[52:53] op_sel_hi:[1,0,1]
	ds_read_b128 v[40:43], v116 offset:2048
	ds_read_b128 v[44:47], v116 offset:2064
	ds_read_b128 v[48:51], v116 offset:2080
	ds_read_b128 v[52:55], v116 offset:2096
	ds_read2_b32 v[100:101], v16 offset0:32 offset1:48
	v_lshl_add_u64 v[90:91], v[90:91], 0, s[44:45]
	v_lshl_add_u64 v[92:93], v[92:93], 0, s[44:45]
	s_waitcnt lgkmcnt(4)
	s_waitcnt vmcnt(7)
	v_pk_fma_f32 v[66:67], v[200:201], v[40:41], v[66:67] op_sel_hi:[1,0,1]
	v_pk_fma_f32 v[64:65], v[198:199], v[40:41], v[64:65] op_sel_hi:[1,0,1]
	v_pk_fma_f32 v[62:63], v[200:201], v[40:41], v[62:63] op_sel:[0,1,0]
	v_pk_fma_f32 v[60:61], v[198:199], v[40:41], v[60:61] op_sel:[0,1,0]
	v_mov_b32_e32 v40, v43
	v_pk_fma_f32 v[104:105], v[198:199], v[40:41], v[110:111] op_sel_hi:[1,0,1]
	v_pk_fma_f32 v[106:107], v[200:201], v[40:41], v[108:109] op_sel_hi:[1,0,1]
	s_waitcnt lgkmcnt(3)
	v_mov_b32_e32 v40, v47
	v_pk_fma_f32 v[56:57], v[198:199], v[42:43], v[56:57] op_sel_hi:[1,0,1]
	v_pk_fma_f32 v[58:59], v[200:201], v[42:43], v[58:59] op_sel_hi:[1,0,1]
	v_pk_fma_f32 v[108:109], v[200:201], v[44:45], v[112:113] op_sel_hi:[1,0,1]
	v_pk_fma_f32 v[110:111], v[198:199], v[44:45], v[130:131] op_sel_hi:[1,0,1]
	v_pk_fma_f32 v[112:113], v[200:201], v[44:45], v[132:133] op_sel:[0,1,0]
	v_pk_fma_f32 v[118:119], v[198:199], v[44:45], v[118:119] op_sel:[0,1,0]
	v_pk_fma_f32 v[122:123], v[198:199], v[46:47], v[134:135] op_sel_hi:[1,0,1]
	v_pk_fma_f32 v[102:103], v[200:201], v[46:47], v[102:103] op_sel_hi:[1,0,1]
	v_pk_fma_f32 v[120:121], v[200:201], v[40:41], v[120:121] op_sel_hi:[1,0,1]
	v_pk_fma_f32 v[124:125], v[198:199], v[40:41], v[136:137] op_sel_hi:[1,0,1]
	s_waitcnt lgkmcnt(0)
	v_pk_mul_f32 v[36:37], v[198:199], v[100:101] op_sel_hi:[1,0]
	v_pk_mul_f32 v[38:39], v[200:201], v[100:101] op_sel_hi:[1,0]
	v_pk_fma_f32 v[36:37], v[0:1], v[48:49], v[36:37] op_sel_hi:[1,0,1]
	v_pk_fma_f32 v[38:39], v[2:3], v[48:49], v[38:39] op_sel_hi:[1,0,1]
	v_pk_fma_f32 v[36:37], v[4:5], v[48:49], v[36:37] op_sel:[0,1,0]
	v_pk_fma_f32 v[38:39], v[6:7], v[48:49], v[38:39] op_sel:[0,1,0]
	v_pk_fma_f32 v[36:37], v[8:9], v[50:51], v[36:37] op_sel_hi:[1,0,1]
	v_pk_fma_f32 v[38:39], v[10:11], v[50:51], v[38:39] op_sel_hi:[1,0,1]
	v_mov_b32_e32 v40, v51
	v_pk_fma_f32 v[36:37], v[12:13], v[40:41], v[36:37] op_sel_hi:[1,0,1]
	v_pk_fma_f32 v[38:39], v[14:15], v[40:41], v[38:39] op_sel_hi:[1,0,1]
	v_pk_fma_f32 v[36:37], v[20:21], v[52:53], v[36:37] op_sel_hi:[1,0,1]
	v_pk_fma_f32 v[38:39], v[22:23], v[52:53], v[38:39] op_sel_hi:[1,0,1]
	v_pk_fma_f32 v[36:37], v[24:25], v[52:53], v[36:37] op_sel:[0,1,0]
	v_pk_fma_f32 v[38:39], v[26:27], v[52:53], v[38:39] op_sel:[0,1,0]
	v_pk_fma_f32 v[36:37], v[28:29], v[54:55], v[36:37] op_sel_hi:[1,0,1]
	v_pk_fma_f32 v[38:39], v[30:31], v[54:55], v[38:39] op_sel_hi:[1,0,1]
	v_mov_b32_e32 v40, v55
	v_pk_fma_f32 v[36:37], v[32:33], v[40:41], v[36:37] op_sel_hi:[1,0,1]
	v_pk_fma_f32 v[38:39], v[34:35], v[40:41], v[38:39] op_sel_hi:[1,0,1]
	v_lshl_add_u64 v[40:41], v[88:89], 0, s[8:9]
	global_store_dwordx4 v[40:41], v[36:39], off nt
	v_lshl_add_u64 v[88:89], v[88:89], 0, s[44:45]
	s_nop 0
	v_lshl_add_u64 v[36:37], v[86:87], 0, s[8:9]
	ds_read_b128 v[40:43], v116 offset:3072
	ds_read_b128 v[44:47], v116 offset:3088
	ds_read_b128 v[48:51], v116 offset:3104
	ds_read_b128 v[52:55], v116 offset:3120
	v_lshl_add_u64 v[86:87], v[86:87], 0, s[44:45]
	s_waitcnt lgkmcnt(3)
	s_waitcnt vmcnt(7)
	v_pk_fma_f32 v[66:67], v[206:207], v[40:41], v[66:67] op_sel_hi:[1,0,1]
	v_pk_fma_f32 v[64:65], v[204:205], v[40:41], v[64:65] op_sel_hi:[1,0,1]
	v_pk_fma_f32 v[62:63], v[206:207], v[40:41], v[62:63] op_sel:[0,1,0]
	v_pk_fma_f32 v[60:61], v[204:205], v[40:41], v[60:61] op_sel:[0,1,0]
	v_mov_b32_e32 v40, v43
	v_pk_fma_f32 v[106:107], v[206:207], v[40:41], v[106:107] op_sel_hi:[1,0,1]
	v_pk_fma_f32 v[104:105], v[204:205], v[40:41], v[104:105] op_sel_hi:[1,0,1]
	s_waitcnt lgkmcnt(2)
; #define LAS __attribute__((address_space(3)))
; template <int TY> __device__ __forceinline__ void sample_item(const Params& p, ldsp lds, int item) {
;     ...
; #pragma unroll 8
;     for (int d = dg; d < DK; d += NG) { const f32x4 s0 = __builtin_nontemporal_load((const f32x4*)(S0 + (size_t)d * DV + e4 * 4));
;         const f32x4 qa = *(const LAS f32x4*)(QK + d * 16), qb = *(const LAS f32x4*)(QK + d * 16 + 4), ka = *(const LAS f32x4*)(QK + d * 16 + 8), kb = *(const LAS f32x4*)(QK + d * 16 + 12);
;         const float dc = DECs[d];
;         o[0] += s0 * qa[0]; o[1] += s0 * qa[1]; o[2] += s0 * qa[2]; o[3] += s0 * qa[3]; o[4] += s0 * qb[0]; o[5] += s0 * qb[1]; o[6] += s0 * qb[2]; o[7] += s0 * qb[3];
;         f32x4 sn = s0 * dc; sn += v[0] * ka[0]; sn += v[1] * ka[1]; sn += v[2] * ka[2]; sn += v[3] * ka[3]; sn += v[4] * kb[0]; sn += v[5] * kb[1]; sn += v[6] * kb[2]; sn += v[7] * kb[3];
;         __builtin_nontemporal_store(sn, (f32x4*)(S1 + (size_t)d * DV + e4 * 4)); }
	v_mov_b32_e32 v40, v47
	v_pk_fma_f32 v[120:121], v[206:207], v[40:41], v[120:121] op_sel_hi:[1,0,1]
	v_pk_fma_f32 v[124:125], v[204:205], v[40:41], v[124:125] op_sel_hi:[1,0,1]
	v_mov_b32_e32 v40, v101
	v_pk_fma_f32 v[58:59], v[206:207], v[42:43], v[58:59] op_sel_hi:[1,0,1]
	v_pk_fma_f32 v[56:57], v[204:205], v[42:43], v[56:57] op_sel_hi:[1,0,1]
	v_pk_fma_f32 v[108:109], v[206:207], v[44:45], v[108:109] op_sel_hi:[1,0,1]
	v_pk_fma_f32 v[110:111], v[204:205], v[44:45], v[110:111] op_sel_hi:[1,0,1]
	v_pk_fma_f32 v[112:113], v[206:207], v[44:45], v[112:113] op_sel:[0,1,0]
	v_pk_fma_f32 v[118:119], v[204:205], v[44:45], v[118:119] op_sel:[0,1,0]
	v_pk_fma_f32 v[102:103], v[206:207], v[46:47], v[102:103] op_sel_hi:[1,0,1]
	v_pk_fma_f32 v[122:123], v[204:205], v[46:47], v[122:123] op_sel_hi:[1,0,1]
	v_pk_mul_f32 v[36:37], v[204:205], v[40:41] op_sel_hi:[1,0]
	v_pk_mul_f32 v[38:39], v[206:207], v[40:41] op_sel_hi:[1,0]
	s_waitcnt lgkmcnt(1)
	v_pk_fma_f32 v[36:37], v[0:1], v[48:49], v[36:37] op_sel_hi:[1,0,1]
	v_pk_fma_f32 v[38:39], v[2:3], v[48:49], v[38:39] op_sel_hi:[1,0,1]
	v_pk_fma_f32 v[36:37], v[4:5], v[48:49], v[36:37] op_sel:[0,1,0]
	v_pk_fma_f32 v[38:39], v[6:7], v[48:49], v[38:39] op_sel:[0,1,0]
	v_pk_fma_f32 v[36:37], v[8:9], v[50:51], v[36:37] op_sel_hi:[1,0,1]
	v_pk_fma_f32 v[38:39], v[10:11], v[50:51], v[38:39] op_sel_hi:[1,0,1]
	v_mov_b32_e32 v40, v51
	v_pk_fma_f32 v[36:37], v[12:13], v[40:41], v[36:37] op_sel_hi:[1,0,1]
	v_pk_fma_f32 v[38:39], v[14:15], v[40:41], v[38:39] op_sel_hi:[1,0,1]
	s_waitcnt lgkmcnt(0)
	v_pk_fma_f32 v[36:37], v[20:21], v[52:53], v[36:37] op_sel_hi:[1,0,1]
	v_pk_fma_f32 v[38:39], v[22:23], v[52:53], v[38:39] op_sel_hi:[1,0,1]
	v_pk_fma_f32 v[36:37], v[24:25], v[52:53], v[36:37] op_sel:[0,1,0]
	v_pk_fma_f32 v[38:39], v[26:27], v[52:53], v[38:39] op_sel:[0,1,0]
	v_pk_fma_f32 v[36:37], v[28:29], v[54:55], v[36:37] op_sel_hi:[1,0,1]
	v_pk_fma_f32 v[38:39], v[30:31], v[54:55], v[38:39] op_sel_hi:[1,0,1]
	v_mov_b32_e32 v40, v55
	v_pk_fma_f32 v[36:37], v[32:33], v[40:41], v[36:37] op_sel_hi:[1,0,1]
	v_pk_fma_f32 v[38:39], v[34:35], v[40:41], v[38:39] op_sel_hi:[1,0,1]
	v_lshl_add_u64 v[40:41], v[84:85], 0, s[8:9]
	global_store_dwordx4 v[40:41], v[36:39], off nt
	v_lshl_add_u64 v[84:85], v[84:85], 0, s[44:45]
	s_nop 0
	v_lshl_add_u64 v[36:37], v[82:83], 0, s[8:9]
	ds_read_b128 v[40:43], v116 offset:4096
	ds_read_b128 v[44:47], v116 offset:4112
	ds_read_b128 v[48:51], v116 offset:4128
	ds_read_b128 v[52:55], v116 offset:4144
	ds_read2_b32 v[100:101], v16 offset0:64 offset1:80
	v_lshl_add_u64 v[82:83], v[82:83], 0, s[44:45]
	s_waitcnt lgkmcnt(4)
	s_waitcnt vmcnt(7)
	v_pk_fma_f32 v[66:67], v[212:213], v[40:41], v[66:67] op_sel_hi:[1,0,1]
	v_pk_fma_f32 v[64:65], v[210:211], v[40:41], v[64:65] op_sel_hi:[1,0,1]
	v_pk_fma_f32 v[62:63], v[212:213], v[40:41], v[62:63] op_sel:[0,1,0]
	v_pk_fma_f32 v[60:61], v[210:211], v[40:41], v[60:61] op_sel:[0,1,0]
	v_mov_b32_e32 v40, v43
	v_pk_fma_f32 v[104:105], v[210:211], v[40:41], v[104:105] op_sel_hi:[1,0,1]
	v_pk_fma_f32 v[106:107], v[212:213], v[40:41], v[106:107] op_sel_hi:[1,0,1]
	s_waitcnt lgkmcnt(3)
	v_mov_b32_e32 v40, v47
	v_pk_fma_f32 v[56:57], v[210:211], v[42:43], v[56:57] op_sel_hi:[1,0,1]
	v_pk_fma_f32 v[58:59], v[212:213], v[42:43], v[58:59] op_sel_hi:[1,0,1]
	v_pk_fma_f32 v[108:109], v[212:213], v[44:45], v[108:109] op_sel_hi:[1,0,1]
	v_pk_fma_f32 v[110:111], v[210:211], v[44:45], v[110:111] op_sel_hi:[1,0,1]
	v_pk_fma_f32 v[112:113], v[212:213], v[44:45], v[112:113] op_sel:[0,1,0]
	v_pk_fma_f32 v[118:119], v[210:211], v[44:45], v[118:119] op_sel:[0,1,0]
	v_pk_fma_f32 v[122:123], v[210:211], v[46:47], v[122:123] op_sel_hi:[1,0,1]
	v_pk_fma_f32 v[102:103], v[212:213], v[46:47], v[102:103] op_sel_hi:[1,0,1]
	v_pk_fma_f32 v[120:121], v[212:213], v[40:41], v[120:121] op_sel_hi:[1,0,1]
	v_pk_fma_f32 v[124:125], v[210:211], v[40:41], v[124:125] op_sel_hi:[1,0,1]
	s_waitcnt lgkmcnt(0)
	v_pk_mul_f32 v[36:37], v[210:211], v[100:101] op_sel_hi:[1,0]
	v_pk_mul_f32 v[38:39], v[212:213], v[100:101] op_sel_hi:[1,0]
	v_pk_fma_f32 v[36:37], v[0:1], v[48:49], v[36:37] op_sel_hi:[1,0,1]
	v_pk_fma_f32 v[38:39], v[2:3], v[48:49], v[38:39] op_sel_hi:[1,0,1]
	v_pk_fma_f32 v[36:37], v[4:5], v[48:49], v[36:37] op_sel:[0,1,0]
	v_pk_fma_f32 v[38:39], v[6:7], v[48:49], v[38:39] op_sel:[0,1,0]
	v_pk_fma_f32 v[36:37], v[8:9], v[50:51], v[36:37] op_sel_hi:[1,0,1]
	v_pk_fma_f32 v[38:39], v[10:11], v[50:51], v[38:39] op_sel_hi:[1,0,1]
	v_mov_b32_e32 v40, v51
	v_pk_fma_f32 v[36:37], v[12:13], v[40:41], v[36:37] op_sel_hi:[1,0,1]
	v_pk_fma_f32 v[38:39], v[14:15], v[40:41], v[38:39] op_sel_hi:[1,0,1]
	v_pk_fma_f32 v[36:37], v[20:21], v[52:53], v[36:37] op_sel_hi:[1,0,1]
	v_pk_fma_f32 v[38:39], v[22:23], v[52:53], v[38:39] op_sel_hi:[1,0,1]
	v_pk_fma_f32 v[36:37], v[24:25], v[52:53], v[36:37] op_sel:[0,1,0]
	v_pk_fma_f32 v[38:39], v[26:27], v[52:53], v[38:39] op_sel:[0,1,0]
	v_pk_fma_f32 v[36:37], v[28:29], v[54:55], v[36:37] op_sel_hi:[1,0,1]
	v_pk_fma_f32 v[38:39], v[30:31], v[54:55], v[38:39] op_sel_hi:[1,0,1]
	v_mov_b32_e32 v40, v55
	v_pk_fma_f32 v[36:37], v[32:33], v[40:41], v[36:37] op_sel_hi:[1,0,1]
	v_pk_fma_f32 v[38:39], v[34:35], v[40:41], v[38:39] op_sel_hi:[1,0,1]
	v_lshl_add_u64 v[40:41], v[80:81], 0, s[8:9]
	global_store_dwordx4 v[40:41], v[36:39], off nt
	v_lshl_add_u64 v[80:81], v[80:81], 0, s[44:45]
	s_nop 0
	v_lshl_add_u64 v[36:37], v[78:79], 0, s[8:9]
	ds_read_b128 v[40:43], v116 offset:5120
	ds_read_b128 v[44:47], v116 offset:5136
	ds_read_b128 v[48:51], v116 offset:5152
	ds_read_b128 v[52:55], v116 offset:5168
	v_lshl_add_u64 v[78:79], v[78:79], 0, s[44:45]
	s_waitcnt lgkmcnt(3)
; #define LAS __attribute__((address_space(3)))
; template <int TY> __device__ __forceinline__ void sample_item(const Params& p, ldsp lds, int item) {
;     ...
; #pragma unroll 8
;     for (int d = dg; d < DK; d += NG) { const f32x4 s0 = __builtin_nontemporal_load((const f32x4*)(S0 + (size_t)d * DV + e4 * 4));
;         const f32x4 qa = *(const LAS f32x4*)(QK + d * 16), qb = *(const LAS f32x4*)(QK + d * 16 + 4), ka = *(const LAS f32x4*)(QK + d * 16 + 8), kb = *(const LAS f32x4*)(QK + d * 16 + 12);
;         const float dc = DECs[d];
;         o[0] += s0 * qa[0]; o[1] += s0 * qa[1]; o[2] += s0 * qa[2]; o[3] += s0 * qa[3]; o[4] += s0 * qb[0]; o[5] += s0 * qb[1]; o[6] += s0 * qb[2]; o[7] += s0 * qb[3];
;         f32x4 sn = s0 * dc; sn += v[0] * ka[0]; sn += v[1] * ka[1]; sn += v[2] * ka[2]; sn += v[3] * ka[3]; sn += v[4] * kb[0]; sn += v[5] * kb[1]; sn += v[6] * kb[2]; sn += v[7] * kb[3];
;         __builtin_nontemporal_store(sn, (f32x4*)(S1 + (size_t)d * DV + e4 * 4)); }
	s_waitcnt vmcnt(7)
	v_pk_fma_f32 v[126:127], v[218:219], v[40:41], v[66:67] op_sel_hi:[1,0,1]
	v_pk_fma_f32 v[128:129], v[216:217], v[40:41], v[64:65] op_sel_hi:[1,0,1]
	v_pk_fma_f32 v[130:131], v[218:219], v[40:41], v[62:63] op_sel:[0,1,0]
	v_pk_fma_f32 v[132:133], v[216:217], v[40:41], v[60:61] op_sel:[0,1,0]
	v_mov_b32_e32 v40, v43
	v_pk_fma_f32 v[106:107], v[218:219], v[40:41], v[106:107] op_sel_hi:[1,0,1]
	v_pk_fma_f32 v[104:105], v[216:217], v[40:41], v[104:105] op_sel_hi:[1,0,1]
	s_waitcnt lgkmcnt(2)
	v_mov_b32_e32 v40, v47
	v_pk_fma_f32 v[140:141], v[218:219], v[40:41], v[120:121] op_sel_hi:[1,0,1]
	v_pk_fma_f32 v[124:125], v[216:217], v[40:41], v[124:125] op_sel_hi:[1,0,1]
	v_mov_b32_e32 v40, v101
	v_pk_fma_f32 v[134:135], v[218:219], v[42:43], v[58:59] op_sel_hi:[1,0,1]
	v_pk_fma_f32 v[136:137], v[216:217], v[42:43], v[56:57] op_sel_hi:[1,0,1]
	v_pk_fma_f32 v[108:109], v[218:219], v[44:45], v[108:109] op_sel_hi:[1,0,1]
	v_pk_fma_f32 v[110:111], v[216:217], v[44:45], v[110:111] op_sel_hi:[1,0,1]
	v_pk_fma_f32 v[112:113], v[218:219], v[44:45], v[112:113] op_sel:[0,1,0]
	v_pk_fma_f32 v[44:45], v[216:217], v[44:45], v[118:119] op_sel:[0,1,0]
	v_pk_fma_f32 v[138:139], v[218:219], v[46:47], v[102:103] op_sel_hi:[1,0,1]
	v_pk_fma_f32 v[122:123], v[216:217], v[46:47], v[122:123] op_sel_hi:[1,0,1]
	v_pk_mul_f32 v[36:37], v[216:217], v[40:41] op_sel_hi:[1,0]
	v_pk_mul_f32 v[38:39], v[218:219], v[40:41] op_sel_hi:[1,0]
	s_waitcnt lgkmcnt(1)
	v_pk_fma_f32 v[36:37], v[0:1], v[48:49], v[36:37] op_sel_hi:[1,0,1]
	v_pk_fma_f32 v[38:39], v[2:3], v[48:49], v[38:39] op_sel_hi:[1,0,1]
	v_pk_fma_f32 v[36:37], v[4:5], v[48:49], v[36:37] op_sel:[0,1,0]
	v_pk_fma_f32 v[38:39], v[6:7], v[48:49], v[38:39] op_sel:[0,1,0]
	v_pk_fma_f32 v[36:37], v[8:9], v[50:51], v[36:37] op_sel_hi:[1,0,1]
	v_pk_fma_f32 v[38:39], v[10:11], v[50:51], v[38:39] op_sel_hi:[1,0,1]
	v_mov_b32_e32 v40, v51
	v_pk_fma_f32 v[36:37], v[12:13], v[40:41], v[36:37] op_sel_hi:[1,0,1]
	v_pk_fma_f32 v[38:39], v[14:15], v[40:41], v[38:39] op_sel_hi:[1,0,1]
	s_waitcnt lgkmcnt(0)
	v_pk_fma_f32 v[36:37], v[20:21], v[52:53], v[36:37] op_sel_hi:[1,0,1]
	v_pk_fma_f32 v[38:39], v[22:23], v[52:53], v[38:39] op_sel_hi:[1,0,1]
	v_pk_fma_f32 v[36:37], v[24:25], v[52:53], v[36:37] op_sel:[0,1,0]
	v_pk_fma_f32 v[38:39], v[26:27], v[52:53], v[38:39] op_sel:[0,1,0]
	v_pk_fma_f32 v[36:37], v[28:29], v[54:55], v[36:37] op_sel_hi:[1,0,1]
	v_pk_fma_f32 v[38:39], v[30:31], v[54:55], v[38:39] op_sel_hi:[1,0,1]
	v_mov_b32_e32 v40, v55
	v_pk_fma_f32 v[36:37], v[32:33], v[40:41], v[36:37] op_sel_hi:[1,0,1]
	v_pk_fma_f32 v[38:39], v[34:35], v[40:41], v[38:39] op_sel_hi:[1,0,1]
	v_lshl_add_u64 v[40:41], v[76:77], 0, s[8:9]
	global_store_dwordx4 v[40:41], v[36:39], off nt
	v_lshl_add_u64 v[76:77], v[76:77], 0, s[44:45]
	s_nop 0
	v_lshl_add_u64 v[36:37], v[74:75], 0, s[8:9]
	ds_read_b128 v[36:39], v116 offset:6144
	ds_read_b128 v[60:63], v116 offset:6160
	ds_read_b128 v[64:67], v116 offset:6176
	ds_read_b128 v[118:121], v116 offset:6192
	ds_read2_b32 v[100:101], v16 offset0:96 offset1:112
	s_waitcnt lgkmcnt(4)
	v_mov_b32_e32 v50, v39
	v_add_u32_e32 v16, 0x200, v16
	v_lshl_add_u64 v[74:75], v[74:75], 0, s[44:45]
	s_waitcnt vmcnt(7)
	v_pk_fma_f32 v[40:41], v[224:225], v[36:37], v[126:127] op_sel_hi:[1,0,1]
	v_pk_fma_f32 v[42:43], v[222:223], v[36:37], v[128:129] op_sel_hi:[1,0,1]
	v_pk_fma_f32 v[46:47], v[224:225], v[36:37], v[130:131] op_sel:[0,1,0]
	v_pk_fma_f32 v[48:49], v[222:223], v[36:37], v[132:133] op_sel:[0,1,0]
	v_pk_fma_f32 v[36:37], v[222:223], v[38:39], v[136:137] op_sel_hi:[1,0,1]
	v_pk_fma_f32 v[52:53], v[224:225], v[38:39], v[134:135] op_sel_hi:[1,0,1]
	v_pk_fma_f32 v[38:39], v[222:223], v[50:51], v[104:105] op_sel_hi:[1,0,1]
	v_pk_fma_f32 v[54:55], v[224:225], v[50:51], v[106:107] op_sel_hi:[1,0,1]
	s_waitcnt lgkmcnt(3)
	v_pk_fma_f32 v[50:51], v[224:225], v[60:61], v[108:109] op_sel_hi:[1,0,1]
	v_pk_fma_f32 v[102:103], v[222:223], v[60:61], v[110:111] op_sel_hi:[1,0,1]
	v_pk_fma_f32 v[104:105], v[224:225], v[60:61], v[112:113] op_sel:[0,1,0]
	v_pk_fma_f32 v[106:107], v[222:223], v[60:61], v[44:45] op_sel:[0,1,0]
	v_mov_b32_e32 v60, v63
	v_pk_fma_f32 v[44:45], v[222:223], v[62:63], v[122:123] op_sel_hi:[1,0,1]
	v_pk_fma_f32 v[112:113], v[224:225], v[62:63], v[138:139] op_sel_hi:[1,0,1]
	v_pk_fma_f32 v[108:109], v[224:225], v[60:61], v[140:141] op_sel_hi:[1,0,1]
	v_pk_fma_f32 v[110:111], v[222:223], v[60:61], v[124:125] op_sel_hi:[1,0,1]
	s_waitcnt lgkmcnt(0)
; #define LAS __attribute__((address_space(3)))
; template <int TY> __device__ __forceinline__ void sample_item(const Params& p, ldsp lds, int item) {
;     ...
; #pragma unroll 8
;     for (int d = dg; d < DK; d += NG) { const f32x4 s0 = __builtin_nontemporal_load((const f32x4*)(S0 + (size_t)d * DV + e4 * 4));
;         const f32x4 qa = *(const LAS f32x4*)(QK + d * 16), qb = *(const LAS f32x4*)(QK + d * 16 + 4), ka = *(const LAS f32x4*)(QK + d * 16 + 8), kb = *(const LAS f32x4*)(QK + d * 16 + 12);
;         const float dc = DECs[d];
;         o[0] += s0 * qa[0]; o[1] += s0 * qa[1]; o[2] += s0 * qa[2]; o[3] += s0 * qa[3]; o[4] += s0 * qb[0]; o[5] += s0 * qb[1]; o[6] += s0 * qb[2]; o[7] += s0 * qb[3];
;         f32x4 sn = s0 * dc; sn += v[0] * ka[0]; sn += v[1] * ka[1]; sn += v[2] * ka[2]; sn += v[3] * ka[3]; sn += v[4] * kb[0]; sn += v[5] * kb[1]; sn += v[6] * kb[2]; sn += v[7] * kb[3];
;         __builtin_nontemporal_store(sn, (f32x4*)(S1 + (size_t)d * DV + e4 * 4)); }
	v_pk_mul_f32 v[56:57], v[222:223], v[100:101] op_sel_hi:[1,0]
	v_pk_mul_f32 v[58:59], v[224:225], v[100:101] op_sel_hi:[1,0]
	v_pk_fma_f32 v[56:57], v[0:1], v[64:65], v[56:57] op_sel_hi:[1,0,1]
	v_pk_fma_f32 v[58:59], v[2:3], v[64:65], v[58:59] op_sel_hi:[1,0,1]
	v_pk_fma_f32 v[56:57], v[4:5], v[64:65], v[56:57] op_sel:[0,1,0]
	v_pk_fma_f32 v[58:59], v[6:7], v[64:65], v[58:59] op_sel:[0,1,0]
	v_pk_fma_f32 v[56:57], v[8:9], v[66:67], v[56:57] op_sel_hi:[1,0,1]
	v_pk_fma_f32 v[58:59], v[10:11], v[66:67], v[58:59] op_sel_hi:[1,0,1]
	v_mov_b32_e32 v60, v67
	v_pk_fma_f32 v[56:57], v[12:13], v[60:61], v[56:57] op_sel_hi:[1,0,1]
	v_pk_fma_f32 v[58:59], v[14:15], v[60:61], v[58:59] op_sel_hi:[1,0,1]
	v_pk_fma_f32 v[56:57], v[20:21], v[118:119], v[56:57] op_sel_hi:[1,0,1]
	v_pk_fma_f32 v[58:59], v[22:23], v[118:119], v[58:59] op_sel_hi:[1,0,1]
	v_pk_fma_f32 v[56:57], v[24:25], v[118:119], v[56:57] op_sel:[0,1,0]
	v_pk_fma_f32 v[58:59], v[26:27], v[118:119], v[58:59] op_sel:[0,1,0]
	v_pk_fma_f32 v[56:57], v[28:29], v[120:121], v[56:57] op_sel_hi:[1,0,1]
	v_pk_fma_f32 v[58:59], v[30:31], v[120:121], v[58:59] op_sel_hi:[1,0,1]
	v_mov_b32_e32 v60, v121
	v_pk_fma_f32 v[56:57], v[32:33], v[60:61], v[56:57] op_sel_hi:[1,0,1]
	v_pk_fma_f32 v[58:59], v[34:35], v[60:61], v[58:59] op_sel_hi:[1,0,1]
	v_lshl_add_u64 v[60:61], v[72:73], 0, s[8:9]
	global_store_dwordx4 v[60:61], v[56:59], off nt
	v_mov_b32_e32 v100, v101
	v_lshl_add_u64 v[72:73], v[72:73], 0, s[44:45]
	v_lshl_add_u64 v[56:57], v[70:71], 0, s[8:9]
	ds_read_b128 v[122:125], v116 offset:7168
	ds_read_b128 v[126:129], v116 offset:7184
	ds_read_b128 v[130:133], v116 offset:7200
	ds_read_b128 v[134:137], v116 offset:7216
	v_add_u32_e32 v116, 0x2000, v116
	v_lshl_add_u64 v[70:71], v[70:71], 0, s[44:45]
	s_waitcnt lgkmcnt(3)
	s_waitcnt vmcnt(7)
	v_pk_fma_f32 v[60:61], v[228:229], v[122:123], v[48:49] op_sel:[0,1,0]
	s_waitcnt lgkmcnt(2)
	v_pk_fma_f32 v[48:49], v[228:229], v[126:127], v[102:103] op_sel_hi:[1,0,1]
	v_pk_mul_f32 v[102:103], v[228:229], v[100:101] op_sel_hi:[1,0]
	v_pk_mul_f32 v[100:101], v[230:231], v[100:101] op_sel_hi:[1,0]
	s_waitcnt lgkmcnt(1)
	v_pk_fma_f32 v[102:103], v[0:1], v[130:131], v[102:103] op_sel_hi:[1,0,1]
	v_pk_fma_f32 v[100:101], v[2:3], v[130:131], v[100:101] op_sel_hi:[1,0,1]
	v_pk_fma_f32 v[102:103], v[4:5], v[130:131], v[102:103] op_sel:[0,1,0]
	v_pk_fma_f32 v[100:101], v[6:7], v[130:131], v[100:101] op_sel:[0,1,0]
	v_pk_fma_f32 v[64:65], v[228:229], v[122:123], v[42:43] op_sel_hi:[1,0,1]
	v_pk_fma_f32 v[42:43], v[230:231], v[126:127], v[104:105] op_sel:[0,1,0]
	v_pk_fma_f32 v[100:101], v[10:11], v[132:133], v[100:101] op_sel_hi:[1,0,1]
	v_pk_fma_f32 v[102:103], v[8:9], v[132:133], v[102:103] op_sel_hi:[1,0,1]
	v_mov_b32_e32 v104, v133
	v_pk_fma_f32 v[102:103], v[12:13], v[104:105], v[102:103] op_sel_hi:[1,0,1]
	v_pk_fma_f32 v[100:101], v[14:15], v[104:105], v[100:101] op_sel_hi:[1,0,1]
	s_waitcnt lgkmcnt(0)
	v_pk_fma_f32 v[102:103], v[20:21], v[134:135], v[102:103] op_sel_hi:[1,0,1]
	v_pk_fma_f32 v[100:101], v[22:23], v[134:135], v[100:101] op_sel_hi:[1,0,1]
	v_pk_fma_f32 v[56:57], v[228:229], v[124:125], v[36:37] op_sel_hi:[1,0,1]
	v_mov_b32_e32 v36, v125
	v_pk_fma_f32 v[102:103], v[24:25], v[134:135], v[102:103] op_sel:[0,1,0]
	v_pk_fma_f32 v[100:101], v[26:27], v[134:135], v[100:101] op_sel:[0,1,0]
	v_pk_fma_f32 v[58:59], v[230:231], v[124:125], v[52:53] op_sel_hi:[1,0,1]
	v_pk_fma_f32 v[54:55], v[230:231], v[36:37], v[54:55] op_sel_hi:[1,0,1]
	v_pk_fma_f32 v[52:53], v[228:229], v[36:37], v[38:39] op_sel_hi:[1,0,1]
	v_pk_fma_f32 v[36:37], v[228:229], v[128:129], v[44:45] op_sel_hi:[1,0,1]
	v_mov_b32_e32 v44, v129
	v_pk_fma_f32 v[104:105], v[30:31], v[136:137], v[100:101] op_sel_hi:[1,0,1]
	v_pk_fma_f32 v[100:101], v[28:29], v[136:137], v[102:103] op_sel_hi:[1,0,1]
	v_mov_b32_e32 v102, v137
	v_pk_fma_f32 v[66:67], v[230:231], v[122:123], v[40:41] op_sel_hi:[1,0,1]
	v_pk_fma_f32 v[62:63], v[230:231], v[122:123], v[46:47] op_sel:[0,1,0]
	v_pk_fma_f32 v[50:51], v[230:231], v[126:127], v[50:51] op_sel_hi:[1,0,1]
	v_pk_fma_f32 v[40:41], v[228:229], v[126:127], v[106:107] op_sel:[0,1,0]
	v_pk_fma_f32 v[38:39], v[230:231], v[128:129], v[112:113] op_sel_hi:[1,0,1]
	v_pk_fma_f32 v[46:47], v[230:231], v[44:45], v[108:109] op_sel_hi:[1,0,1]
	v_pk_fma_f32 v[44:45], v[228:229], v[44:45], v[110:111] op_sel_hi:[1,0,1]
	v_pk_fma_f32 v[100:101], v[32:33], v[102:103], v[100:101] op_sel_hi:[1,0,1]
	v_pk_fma_f32 v[102:103], v[34:35], v[102:103], v[104:105] op_sel_hi:[1,0,1]
	v_lshl_add_u64 v[104:105], v[18:19], 0, s[8:9]
	v_lshl_add_u64 v[18:19], v[18:19], 0, s[44:45]
	global_store_dwordx4 v[104:105], v[100:103], off nt
	s_andn2_b64 exec, exec, s[16:17]
	v_mov_b32_e32 v118, v228
	v_mov_b32_e32 v119, v229
	v_mov_b32_e32 v120, v230
	v_mov_b32_e32 v121, v231
	s_cbranch_execnz .LBB0_1005
	s_or_b64 exec, exec, s[16:17]

; #define LAS __attribute__((address_space(3)))
; template <int TY> __device__ __forceinline__ void sample_item(const Params& p, ldsp lds, int item) {
;     ...
; #pragma unroll 8
;     for (int d = dg; d < DK; d += NG) { const f32x4 s0 = __builtin_nontemporal_load((const f32x4*)(S0 + (size_t)d * DV + e4 * 4));
;         const f32x4 qa = *(const LAS f32x4*)(QK + d * 16), qb = *(const LAS f32x4*)(QK + d * 16 + 4), ka = *(const LAS f32x4*)(QK + d * 16 + 8), kb = *(const LAS f32x4*)(QK + d * 16 + 12);
;         const float dc = DECs[d];
;         o[0] += s0 * qa[0]; o[1] += s0 * qa[1]; o[2] += s0 * qa[2]; o[3] += s0 * qa[3]; o[4] += s0 * qb[0]; o[5] += s0 * qb[1]; o[6] += s0 * qb[2]; o[7] += s0 * qb[3];
;         f32x4 sn = s0 * dc; sn += v[0] * ka[0]; sn += v[1] * ka[1]; sn += v[2] * ka[2]; sn += v[3] * ka[3]; sn += v[4] * kb[0]; sn += v[5] * kb[1]; sn += v[6] * kb[2]; sn += v[7] * kb[3];
;         __builtin_nontemporal_store(sn, (f32x4*)(S1 + (size_t)d * DV + e4 * 4)); }
.LBB0_1039:
	v_lshl_add_u64 v[144:145], v[98:99], 0, v[18:19]
	global_load_dwordx4 v[146:149], v[144:145], off nt
	v_lshl_add_u64 v[150:151], v[96:97], 0, v[18:19]
	global_load_dwordx4 v[152:155], v[150:151], off nt
	v_lshl_add_u64 v[156:157], v[92:93], 0, v[18:19]
	global_load_dwordx4 v[166:169], v[156:157], off nt
	v_lshl_add_u64 v[172:173], v[88:89], 0, v[18:19]
	global_load_dwordx4 v[174:177], v[172:173], off nt
	v_lshl_add_u64 v[178:179], v[84:85], 0, v[18:19]
	global_load_dwordx4 v[180:183], v[178:179], off nt
	v_lshl_add_u64 v[186:187], v[80:81], 0, v[18:19]
	global_load_dwordx4 v[188:191], v[186:187], off nt
	v_lshl_add_u64 v[192:193], v[76:77], 0, v[18:19]
	global_load_dwordx4 v[194:197], v[192:193], off nt
	v_lshl_add_u64 v[198:199], v[72:73], 0, v[18:19]
	global_load_dwordx4 v[206:209], v[198:199], off nt
	v_lshl_add_u64 v[102:103], v[98:99], 0, v[18:19]
	s_nop 0
	ds_read_b128 v[110:113], v118
	ds_read_b128 v[120:123], v118 offset:16
	ds_read_b128 v[124:127], v118 offset:32
	ds_read_b128 v[128:131], v118 offset:48
	ds_read2_b32 v[102:103], v16 offset1:16
	s_waitcnt lgkmcnt(0)
	v_mov_b32_e32 v104, v113
	v_add_u32_e32 v69, 0x80, v69
	s_movk_i32 s18, 0xffbf
	v_cmp_lt_i32_e32 vcc, s18, v69
	v_lshl_add_u64 v[98:99], v[98:99], 0, s[44:45]
	s_or_b64 s[10:11], vcc, s[10:11]
	s_nop 0
	s_waitcnt vmcnt(7)
	v_pk_fma_f32 v[64:65], v[146:147], v[110:111], v[64:65] op_sel_hi:[1,0,1]
	v_pk_fma_f32 v[66:67], v[148:149], v[110:111], v[66:67] op_sel_hi:[1,0,1]
	v_pk_fma_f32 v[60:61], v[146:147], v[110:111], v[60:61] op_sel:[0,1,0]
	v_pk_fma_f32 v[62:63], v[148:149], v[110:111], v[62:63] op_sel:[0,1,0]
	v_mov_b32_e32 v110, v123
	v_pk_fma_f32 v[56:57], v[146:147], v[112:113], v[56:57] op_sel_hi:[1,0,1]
	v_pk_fma_f32 v[52:53], v[146:147], v[104:105], v[52:53] op_sel_hi:[1,0,1]
	v_pk_fma_f32 v[54:55], v[148:149], v[104:105], v[54:55] op_sel_hi:[1,0,1]
	v_pk_fma_f32 v[48:49], v[146:147], v[120:121], v[48:49] op_sel_hi:[1,0,1]
	v_pk_fma_f32 v[40:41], v[146:147], v[120:121], v[40:41] op_sel:[0,1,0]
	v_pk_fma_f32 v[36:37], v[146:147], v[122:123], v[36:37] op_sel_hi:[1,0,1]
	v_pk_fma_f32 v[104:105], v[148:149], v[122:123], v[38:39] op_sel_hi:[1,0,1]
	v_pk_fma_f32 v[38:39], v[146:147], v[110:111], v[44:45] op_sel_hi:[1,0,1]
	v_pk_fma_f32 v[44:45], v[148:149], v[110:111], v[46:47] op_sel_hi:[1,0,1]
	v_pk_mul_f32 v[46:47], v[146:147], v[102:103] op_sel_hi:[1,0]
	v_pk_mul_f32 v[106:107], v[148:149], v[102:103] op_sel_hi:[1,0]
	v_pk_fma_f32 v[46:47], v[0:1], v[124:125], v[46:47] op_sel_hi:[1,0,1]
	v_pk_fma_f32 v[106:107], v[2:3], v[124:125], v[106:107] op_sel_hi:[1,0,1]
	v_pk_fma_f32 v[46:47], v[4:5], v[124:125], v[46:47] op_sel:[0,1,0]
	v_pk_fma_f32 v[106:107], v[6:7], v[124:125], v[106:107] op_sel:[0,1,0]
	v_pk_fma_f32 v[46:47], v[8:9], v[126:127], v[46:47] op_sel_hi:[1,0,1]
	v_pk_fma_f32 v[106:107], v[10:11], v[126:127], v[106:107] op_sel_hi:[1,0,1]
	v_mov_b32_e32 v102, v127
	v_pk_fma_f32 v[46:47], v[12:13], v[102:103], v[46:47] op_sel_hi:[1,0,1]
	v_pk_fma_f32 v[106:107], v[14:15], v[102:103], v[106:107] op_sel_hi:[1,0,1]
	v_pk_fma_f32 v[46:47], v[20:21], v[128:129], v[46:47] op_sel_hi:[1,0,1]
	v_pk_fma_f32 v[106:107], v[22:23], v[128:129], v[106:107] op_sel_hi:[1,0,1]
	v_pk_fma_f32 v[46:47], v[24:25], v[128:129], v[46:47] op_sel:[0,1,0]
	v_pk_fma_f32 v[106:107], v[26:27], v[128:129], v[106:107] op_sel:[0,1,0]
	v_pk_fma_f32 v[58:59], v[148:149], v[112:113], v[58:59] op_sel_hi:[1,0,1]
	v_pk_fma_f32 v[50:51], v[148:149], v[120:121], v[50:51] op_sel_hi:[1,0,1]
	v_pk_fma_f32 v[42:43], v[148:149], v[120:121], v[42:43] op_sel:[0,1,0]
	v_pk_fma_f32 v[108:109], v[30:31], v[130:131], v[106:107] op_sel_hi:[1,0,1]
	v_pk_fma_f32 v[46:47], v[28:29], v[130:131], v[46:47] op_sel_hi:[1,0,1]
	v_mov_b32_e32 v102, v131
	v_pk_fma_f32 v[106:107], v[32:33], v[102:103], v[46:47] op_sel_hi:[1,0,1]
	v_pk_fma_f32 v[108:109], v[34:35], v[102:103], v[108:109] op_sel_hi:[1,0,1]
	v_lshl_add_u64 v[46:47], v[100:101], 0, v[18:19]
	global_store_dwordx4 v[46:47], v[106:109], off nt
	v_lshl_add_u64 v[46:47], v[96:97], 0, v[18:19]
	s_nop 0
	ds_read_b128 v[110:113], v118 offset:1024
	ds_read_b128 v[120:123], v118 offset:1040
	ds_read_b128 v[124:127], v118 offset:1056
	ds_read_b128 v[128:131], v118 offset:1072
	v_lshl_add_u64 v[96:97], v[96:97], 0, s[44:45]
	s_waitcnt lgkmcnt(3)
	v_mov_b32_e32 v46, v113
	v_lshl_add_u64 v[100:101], v[100:101], 0, s[44:45]
	s_waitcnt lgkmcnt(2)
	s_waitcnt vmcnt(7)
	v_pk_fma_f32 v[136:137], v[152:153], v[122:123], v[36:37] op_sel_hi:[1,0,1]
	v_mov_b32_e32 v36, v123
	v_pk_fma_f32 v[104:105], v[154:155], v[122:123], v[104:105] op_sel_hi:[1,0,1]
	v_pk_fma_f32 v[122:123], v[154:155], v[36:37], v[44:45] op_sel_hi:[1,0,1]
	v_pk_fma_f32 v[138:139], v[152:153], v[36:37], v[38:39] op_sel_hi:[1,0,1]
	v_mov_b32_e32 v36, v103
	v_pk_mul_f32 v[38:39], v[152:153], v[36:37] op_sel_hi:[1,0]
	v_pk_mul_f32 v[36:37], v[154:155], v[36:37] op_sel_hi:[1,0]
	s_waitcnt lgkmcnt(1)
	v_pk_fma_f32 v[38:39], v[0:1], v[124:125], v[38:39] op_sel_hi:[1,0,1]
	v_pk_fma_f32 v[36:37], v[2:3], v[124:125], v[36:37] op_sel_hi:[1,0,1]
	v_pk_fma_f32 v[38:39], v[4:5], v[124:125], v[38:39] op_sel:[0,1,0]
	v_pk_fma_f32 v[36:37], v[6:7], v[124:125], v[36:37] op_sel:[0,1,0]
	v_pk_fma_f32 v[114:115], v[154:155], v[120:121], v[50:51] op_sel_hi:[1,0,1]
	v_pk_fma_f32 v[132:133], v[152:153], v[120:121], v[48:49] op_sel_hi:[1,0,1]
	v_pk_fma_f32 v[134:135], v[154:155], v[120:121], v[42:43] op_sel:[0,1,0]
	v_pk_fma_f32 v[120:121], v[152:153], v[120:121], v[40:41] op_sel:[0,1,0]
	v_pk_fma_f32 v[36:37], v[10:11], v[126:127], v[36:37] op_sel_hi:[1,0,1]
	v_pk_fma_f32 v[38:39], v[8:9], v[126:127], v[38:39] op_sel_hi:[1,0,1]
	v_mov_b32_e32 v40, v127
	v_pk_fma_f32 v[38:39], v[12:13], v[40:41], v[38:39] op_sel_hi:[1,0,1]
	v_pk_fma_f32 v[36:37], v[14:15], v[40:41], v[36:37] op_sel_hi:[1,0,1]
	s_waitcnt lgkmcnt(0)
; #define LAS __attribute__((address_space(3)))
; template <int TY> __device__ __forceinline__ void sample_item(const Params& p, ldsp lds, int item) {
;     ...
; #pragma unroll 8
;     for (int d = dg; d < DK; d += NG) { const f32x4 s0 = __builtin_nontemporal_load((const f32x4*)(S0 + (size_t)d * DV + e4 * 4));
;         const f32x4 qa = *(const LAS f32x4*)(QK + d * 16), qb = *(const LAS f32x4*)(QK + d * 16 + 4), ka = *(const LAS f32x4*)(QK + d * 16 + 8), kb = *(const LAS f32x4*)(QK + d * 16 + 12);
;         const float dc = DECs[d];
;         o[0] += s0 * qa[0]; o[1] += s0 * qa[1]; o[2] += s0 * qa[2]; o[3] += s0 * qa[3]; o[4] += s0 * qb[0]; o[5] += s0 * qb[1]; o[6] += s0 * qb[2]; o[7] += s0 * qb[3];
;         f32x4 sn = s0 * dc; sn += v[0] * ka[0]; sn += v[1] * ka[1]; sn += v[2] * ka[2]; sn += v[3] * ka[3]; sn += v[4] * kb[0]; sn += v[5] * kb[1]; sn += v[6] * kb[2]; sn += v[7] * kb[3];
;         __builtin_nontemporal_store(sn, (f32x4*)(S1 + (size_t)d * DV + e4 * 4)); }
	v_pk_fma_f32 v[38:39], v[20:21], v[128:129], v[38:39] op_sel_hi:[1,0,1]
	v_pk_fma_f32 v[36:37], v[22:23], v[128:129], v[36:37] op_sel_hi:[1,0,1]
	v_pk_fma_f32 v[38:39], v[24:25], v[128:129], v[38:39] op_sel:[0,1,0]
	v_pk_fma_f32 v[36:37], v[26:27], v[128:129], v[36:37] op_sel:[0,1,0]
	v_pk_fma_f32 v[66:67], v[154:155], v[110:111], v[66:67] op_sel_hi:[1,0,1]
	v_pk_fma_f32 v[40:41], v[30:31], v[130:131], v[36:37] op_sel_hi:[1,0,1]
	v_pk_fma_f32 v[36:37], v[28:29], v[130:131], v[38:39] op_sel_hi:[1,0,1]
	v_mov_b32_e32 v38, v131
	v_pk_fma_f32 v[36:37], v[32:33], v[38:39], v[36:37] op_sel_hi:[1,0,1]
	v_pk_fma_f32 v[38:39], v[34:35], v[38:39], v[40:41] op_sel_hi:[1,0,1]
	v_lshl_add_u64 v[40:41], v[94:95], 0, v[18:19]
	global_store_dwordx4 v[40:41], v[36:39], off nt
	v_pk_fma_f32 v[64:65], v[152:153], v[110:111], v[64:65] op_sel_hi:[1,0,1]
	v_pk_fma_f32 v[62:63], v[154:155], v[110:111], v[62:63] op_sel:[0,1,0]
	v_lshl_add_u64 v[36:37], v[92:93], 0, v[18:19]
	s_nop 0
	v_pk_fma_f32 v[60:61], v[152:153], v[110:111], v[60:61] op_sel:[0,1,0]
	v_pk_fma_f32 v[58:59], v[154:155], v[112:113], v[58:59] op_sel_hi:[1,0,1]
	v_pk_fma_f32 v[56:57], v[152:153], v[112:113], v[56:57] op_sel_hi:[1,0,1]
	v_pk_fma_f32 v[110:111], v[154:155], v[46:47], v[54:55] op_sel_hi:[1,0,1]
	v_pk_fma_f32 v[112:113], v[152:153], v[46:47], v[52:53] op_sel_hi:[1,0,1]
	ds_read_b128 v[40:43], v118 offset:2048
	ds_read_b128 v[44:47], v118 offset:2064
	ds_read_b128 v[48:51], v118 offset:2080
	ds_read_b128 v[52:55], v118 offset:2096
	ds_read2_b32 v[102:103], v16 offset0:32 offset1:48
	v_lshl_add_u64 v[92:93], v[92:93], 0, s[44:45]
	v_lshl_add_u64 v[94:95], v[94:95], 0, s[44:45]
	s_waitcnt lgkmcnt(4)
	s_waitcnt vmcnt(7)
	v_pk_fma_f32 v[66:67], v[168:169], v[40:41], v[66:67] op_sel_hi:[1,0,1]
	v_pk_fma_f32 v[64:65], v[166:167], v[40:41], v[64:65] op_sel_hi:[1,0,1]
	v_pk_fma_f32 v[62:63], v[168:169], v[40:41], v[62:63] op_sel:[0,1,0]
	v_pk_fma_f32 v[60:61], v[166:167], v[40:41], v[60:61] op_sel:[0,1,0]
	v_mov_b32_e32 v40, v43
	v_pk_fma_f32 v[106:107], v[166:167], v[40:41], v[112:113] op_sel_hi:[1,0,1]
	v_pk_fma_f32 v[108:109], v[168:169], v[40:41], v[110:111] op_sel_hi:[1,0,1]
	s_waitcnt lgkmcnt(3)
	v_mov_b32_e32 v40, v47
	v_pk_fma_f32 v[56:57], v[166:167], v[42:43], v[56:57] op_sel_hi:[1,0,1]
	v_pk_fma_f32 v[58:59], v[168:169], v[42:43], v[58:59] op_sel_hi:[1,0,1]
	v_pk_fma_f32 v[110:111], v[168:169], v[44:45], v[114:115] op_sel_hi:[1,0,1]
	v_pk_fma_f32 v[112:113], v[166:167], v[44:45], v[132:133] op_sel_hi:[1,0,1]
	v_pk_fma_f32 v[114:115], v[168:169], v[44:45], v[134:135] op_sel:[0,1,0]
	v_pk_fma_f32 v[120:121], v[166:167], v[44:45], v[120:121] op_sel:[0,1,0]
	v_pk_fma_f32 v[124:125], v[166:167], v[46:47], v[136:137] op_sel_hi:[1,0,1]
	v_pk_fma_f32 v[104:105], v[168:169], v[46:47], v[104:105] op_sel_hi:[1,0,1]
	v_pk_fma_f32 v[122:123], v[168:169], v[40:41], v[122:123] op_sel_hi:[1,0,1]
	v_pk_fma_f32 v[126:127], v[166:167], v[40:41], v[138:139] op_sel_hi:[1,0,1]
	s_waitcnt lgkmcnt(0)
	v_pk_mul_f32 v[36:37], v[166:167], v[102:103] op_sel_hi:[1,0]
	v_pk_mul_f32 v[38:39], v[168:169], v[102:103] op_sel_hi:[1,0]
	v_pk_fma_f32 v[36:37], v[0:1], v[48:49], v[36:37] op_sel_hi:[1,0,1]
	v_pk_fma_f32 v[38:39], v[2:3], v[48:49], v[38:39] op_sel_hi:[1,0,1]
	v_pk_fma_f32 v[36:37], v[4:5], v[48:49], v[36:37] op_sel:[0,1,0]
	v_pk_fma_f32 v[38:39], v[6:7], v[48:49], v[38:39] op_sel:[0,1,0]
	v_pk_fma_f32 v[36:37], v[8:9], v[50:51], v[36:37] op_sel_hi:[1,0,1]
	v_pk_fma_f32 v[38:39], v[10:11], v[50:51], v[38:39] op_sel_hi:[1,0,1]
	v_mov_b32_e32 v40, v51
	v_pk_fma_f32 v[36:37], v[12:13], v[40:41], v[36:37] op_sel_hi:[1,0,1]
	v_pk_fma_f32 v[38:39], v[14:15], v[40:41], v[38:39] op_sel_hi:[1,0,1]
	v_pk_fma_f32 v[36:37], v[20:21], v[52:53], v[36:37] op_sel_hi:[1,0,1]
	v_pk_fma_f32 v[38:39], v[22:23], v[52:53], v[38:39] op_sel_hi:[1,0,1]
	v_pk_fma_f32 v[36:37], v[24:25], v[52:53], v[36:37] op_sel:[0,1,0]
	v_pk_fma_f32 v[38:39], v[26:27], v[52:53], v[38:39] op_sel:[0,1,0]
	v_pk_fma_f32 v[36:37], v[28:29], v[54:55], v[36:37] op_sel_hi:[1,0,1]
	v_pk_fma_f32 v[38:39], v[30:31], v[54:55], v[38:39] op_sel_hi:[1,0,1]
	v_mov_b32_e32 v40, v55
	v_pk_fma_f32 v[36:37], v[32:33], v[40:41], v[36:37] op_sel_hi:[1,0,1]
	v_pk_fma_f32 v[38:39], v[34:35], v[40:41], v[38:39] op_sel_hi:[1,0,1]
	v_lshl_add_u64 v[40:41], v[90:91], 0, v[18:19]
	global_store_dwordx4 v[40:41], v[36:39], off nt
	v_lshl_add_u64 v[90:91], v[90:91], 0, s[44:45]
	s_nop 0
	v_lshl_add_u64 v[36:37], v[88:89], 0, v[18:19]
	s_nop 0
	ds_read_b128 v[40:43], v118 offset:3072
	ds_read_b128 v[44:47], v118 offset:3088
	ds_read_b128 v[48:51], v118 offset:3104
	ds_read_b128 v[52:55], v118 offset:3120
	v_lshl_add_u64 v[88:89], v[88:89], 0, s[44:45]
	s_waitcnt lgkmcnt(3)
	s_waitcnt vmcnt(7)
	v_pk_fma_f32 v[66:67], v[176:177], v[40:41], v[66:67] op_sel_hi:[1,0,1]
	v_pk_fma_f32 v[64:65], v[174:175], v[40:41], v[64:65] op_sel_hi:[1,0,1]
	v_pk_fma_f32 v[62:63], v[176:177], v[40:41], v[62:63] op_sel:[0,1,0]
	v_pk_fma_f32 v[60:61], v[174:175], v[40:41], v[60:61] op_sel:[0,1,0]
	v_mov_b32_e32 v40, v43
	v_pk_fma_f32 v[108:109], v[176:177], v[40:41], v[108:109] op_sel_hi:[1,0,1]
	v_pk_fma_f32 v[106:107], v[174:175], v[40:41], v[106:107] op_sel_hi:[1,0,1]
	s_waitcnt lgkmcnt(2)
; #define LAS __attribute__((address_space(3)))
; template <int TY> __device__ __forceinline__ void sample_item(const Params& p, ldsp lds, int item) {
;     ...
; #pragma unroll 8
;     for (int d = dg; d < DK; d += NG) { const f32x4 s0 = __builtin_nontemporal_load((const f32x4*)(S0 + (size_t)d * DV + e4 * 4));
;         const f32x4 qa = *(const LAS f32x4*)(QK + d * 16), qb = *(const LAS f32x4*)(QK + d * 16 + 4), ka = *(const LAS f32x4*)(QK + d * 16 + 8), kb = *(const LAS f32x4*)(QK + d * 16 + 12);
;         const float dc = DECs[d];
;         o[0] += s0 * qa[0]; o[1] += s0 * qa[1]; o[2] += s0 * qa[2]; o[3] += s0 * qa[3]; o[4] += s0 * qb[0]; o[5] += s0 * qb[1]; o[6] += s0 * qb[2]; o[7] += s0 * qb[3];
;         f32x4 sn = s0 * dc; sn += v[0] * ka[0]; sn += v[1] * ka[1]; sn += v[2] * ka[2]; sn += v[3] * ka[3]; sn += v[4] * kb[0]; sn += v[5] * kb[1]; sn += v[6] * kb[2]; sn += v[7] * kb[3];
;         __builtin_nontemporal_store(sn, (f32x4*)(S1 + (size_t)d * DV + e4 * 4)); }
	v_mov_b32_e32 v40, v47
	v_pk_fma_f32 v[122:123], v[176:177], v[40:41], v[122:123] op_sel_hi:[1,0,1]
	v_pk_fma_f32 v[126:127], v[174:175], v[40:41], v[126:127] op_sel_hi:[1,0,1]
	v_mov_b32_e32 v40, v103
	v_pk_fma_f32 v[58:59], v[176:177], v[42:43], v[58:59] op_sel_hi:[1,0,1]
	v_pk_fma_f32 v[56:57], v[174:175], v[42:43], v[56:57] op_sel_hi:[1,0,1]
	v_pk_fma_f32 v[110:111], v[176:177], v[44:45], v[110:111] op_sel_hi:[1,0,1]
	v_pk_fma_f32 v[112:113], v[174:175], v[44:45], v[112:113] op_sel_hi:[1,0,1]
	v_pk_fma_f32 v[114:115], v[176:177], v[44:45], v[114:115] op_sel:[0,1,0]
	v_pk_fma_f32 v[120:121], v[174:175], v[44:45], v[120:121] op_sel:[0,1,0]
	v_pk_fma_f32 v[104:105], v[176:177], v[46:47], v[104:105] op_sel_hi:[1,0,1]
	v_pk_fma_f32 v[124:125], v[174:175], v[46:47], v[124:125] op_sel_hi:[1,0,1]
	v_pk_mul_f32 v[36:37], v[174:175], v[40:41] op_sel_hi:[1,0]
	v_pk_mul_f32 v[38:39], v[176:177], v[40:41] op_sel_hi:[1,0]
	s_waitcnt lgkmcnt(1)
	v_pk_fma_f32 v[36:37], v[0:1], v[48:49], v[36:37] op_sel_hi:[1,0,1]
	v_pk_fma_f32 v[38:39], v[2:3], v[48:49], v[38:39] op_sel_hi:[1,0,1]
	v_pk_fma_f32 v[36:37], v[4:5], v[48:49], v[36:37] op_sel:[0,1,0]
	v_pk_fma_f32 v[38:39], v[6:7], v[48:49], v[38:39] op_sel:[0,1,0]
	v_pk_fma_f32 v[36:37], v[8:9], v[50:51], v[36:37] op_sel_hi:[1,0,1]
	v_pk_fma_f32 v[38:39], v[10:11], v[50:51], v[38:39] op_sel_hi:[1,0,1]
	v_mov_b32_e32 v40, v51
	v_pk_fma_f32 v[36:37], v[12:13], v[40:41], v[36:37] op_sel_hi:[1,0,1]
	v_pk_fma_f32 v[38:39], v[14:15], v[40:41], v[38:39] op_sel_hi:[1,0,1]
	s_waitcnt lgkmcnt(0)
	v_pk_fma_f32 v[36:37], v[20:21], v[52:53], v[36:37] op_sel_hi:[1,0,1]
	v_pk_fma_f32 v[38:39], v[22:23], v[52:53], v[38:39] op_sel_hi:[1,0,1]
	v_pk_fma_f32 v[36:37], v[24:25], v[52:53], v[36:37] op_sel:[0,1,0]
	v_pk_fma_f32 v[38:39], v[26:27], v[52:53], v[38:39] op_sel:[0,1,0]
	v_pk_fma_f32 v[36:37], v[28:29], v[54:55], v[36:37] op_sel_hi:[1,0,1]
	v_pk_fma_f32 v[38:39], v[30:31], v[54:55], v[38:39] op_sel_hi:[1,0,1]
	v_mov_b32_e32 v40, v55
	v_pk_fma_f32 v[36:37], v[32:33], v[40:41], v[36:37] op_sel_hi:[1,0,1]
	v_pk_fma_f32 v[38:39], v[34:35], v[40:41], v[38:39] op_sel_hi:[1,0,1]
	v_lshl_add_u64 v[40:41], v[86:87], 0, v[18:19]
	global_store_dwordx4 v[40:41], v[36:39], off nt
	v_lshl_add_u64 v[86:87], v[86:87], 0, s[44:45]
	s_nop 0
	v_lshl_add_u64 v[36:37], v[84:85], 0, v[18:19]
	s_nop 0
	ds_read_b128 v[40:43], v118 offset:4096
	ds_read_b128 v[44:47], v118 offset:4112
	ds_read_b128 v[48:51], v118 offset:4128
	ds_read_b128 v[52:55], v118 offset:4144
	ds_read2_b32 v[128:129], v16 offset0:64 offset1:80
	v_lshl_add_u64 v[84:85], v[84:85], 0, s[44:45]
	s_waitcnt lgkmcnt(4)
	s_waitcnt vmcnt(7)
	v_pk_fma_f32 v[66:67], v[182:183], v[40:41], v[66:67] op_sel_hi:[1,0,1]
	v_pk_fma_f32 v[130:131], v[180:181], v[40:41], v[64:65] op_sel_hi:[1,0,1]
	v_pk_fma_f32 v[132:133], v[182:183], v[40:41], v[62:63] op_sel:[0,1,0]
	v_pk_fma_f32 v[60:61], v[180:181], v[40:41], v[60:61] op_sel:[0,1,0]
	v_mov_b32_e32 v40, v43
	v_pk_fma_f32 v[134:135], v[180:181], v[40:41], v[106:107] op_sel_hi:[1,0,1]
	v_pk_fma_f32 v[136:137], v[182:183], v[40:41], v[108:109] op_sel_hi:[1,0,1]
	s_waitcnt lgkmcnt(3)
	v_mov_b32_e32 v40, v47
	v_pk_fma_f32 v[56:57], v[180:181], v[42:43], v[56:57] op_sel_hi:[1,0,1]
	v_pk_fma_f32 v[58:59], v[182:183], v[42:43], v[58:59] op_sel_hi:[1,0,1]
	v_pk_fma_f32 v[110:111], v[182:183], v[44:45], v[110:111] op_sel_hi:[1,0,1]
	v_pk_fma_f32 v[138:139], v[180:181], v[44:45], v[112:113] op_sel_hi:[1,0,1]
	v_pk_fma_f32 v[140:141], v[182:183], v[44:45], v[114:115] op_sel:[0,1,0]
	v_pk_fma_f32 v[120:121], v[180:181], v[44:45], v[120:121] op_sel:[0,1,0]
	v_pk_fma_f32 v[124:125], v[180:181], v[46:47], v[124:125] op_sel_hi:[1,0,1]
	v_pk_fma_f32 v[142:143], v[182:183], v[46:47], v[104:105] op_sel_hi:[1,0,1]
	v_pk_fma_f32 v[122:123], v[182:183], v[40:41], v[122:123] op_sel_hi:[1,0,1]
	v_pk_fma_f32 v[126:127], v[180:181], v[40:41], v[126:127] op_sel_hi:[1,0,1]
	s_waitcnt lgkmcnt(0)
	v_pk_mul_f32 v[36:37], v[180:181], v[128:129] op_sel_hi:[1,0]
	v_pk_mul_f32 v[38:39], v[182:183], v[128:129] op_sel_hi:[1,0]
	v_pk_fma_f32 v[36:37], v[0:1], v[48:49], v[36:37] op_sel_hi:[1,0,1]
	v_pk_fma_f32 v[38:39], v[2:3], v[48:49], v[38:39] op_sel_hi:[1,0,1]
	v_pk_fma_f32 v[36:37], v[4:5], v[48:49], v[36:37] op_sel:[0,1,0]
	v_pk_fma_f32 v[38:39], v[6:7], v[48:49], v[38:39] op_sel:[0,1,0]
	v_pk_fma_f32 v[36:37], v[8:9], v[50:51], v[36:37] op_sel_hi:[1,0,1]
	v_pk_fma_f32 v[38:39], v[10:11], v[50:51], v[38:39] op_sel_hi:[1,0,1]
	v_mov_b32_e32 v40, v51
	v_pk_fma_f32 v[36:37], v[12:13], v[40:41], v[36:37] op_sel_hi:[1,0,1]
	v_pk_fma_f32 v[38:39], v[14:15], v[40:41], v[38:39] op_sel_hi:[1,0,1]
	v_pk_fma_f32 v[36:37], v[20:21], v[52:53], v[36:37] op_sel_hi:[1,0,1]
	v_pk_fma_f32 v[38:39], v[22:23], v[52:53], v[38:39] op_sel_hi:[1,0,1]
	v_pk_fma_f32 v[36:37], v[24:25], v[52:53], v[36:37] op_sel:[0,1,0]
	v_pk_fma_f32 v[38:39], v[26:27], v[52:53], v[38:39] op_sel:[0,1,0]
	v_pk_fma_f32 v[36:37], v[28:29], v[54:55], v[36:37] op_sel_hi:[1,0,1]
	v_pk_fma_f32 v[38:39], v[30:31], v[54:55], v[38:39] op_sel_hi:[1,0,1]
	v_mov_b32_e32 v40, v55
	v_pk_fma_f32 v[36:37], v[32:33], v[40:41], v[36:37] op_sel_hi:[1,0,1]
	v_pk_fma_f32 v[38:39], v[34:35], v[40:41], v[38:39] op_sel_hi:[1,0,1]
	v_lshl_add_u64 v[40:41], v[82:83], 0, v[18:19]
	global_store_dwordx4 v[40:41], v[36:39], off nt
	v_lshl_add_u64 v[82:83], v[82:83], 0, s[44:45]
	s_nop 0
	v_lshl_add_u64 v[36:37], v[80:81], 0, v[18:19]
	s_nop 0
	ds_read_b128 v[38:41], v118 offset:5120
	ds_read_b128 v[62:65], v118 offset:5136
	ds_read_b128 v[106:109], v118 offset:5152
	ds_read_b128 v[112:115], v118 offset:5168
	v_lshl_add_u64 v[80:81], v[80:81], 0, s[44:45]
	s_waitcnt lgkmcnt(3)
; #define LAS __attribute__((address_space(3)))
; template <int TY> __device__ __forceinline__ void sample_item(const Params& p, ldsp lds, int item) {
;     ...
; #pragma unroll 8
;     for (int d = dg; d < DK; d += NG) { const f32x4 s0 = __builtin_nontemporal_load((const f32x4*)(S0 + (size_t)d * DV + e4 * 4));
;         const f32x4 qa = *(const LAS f32x4*)(QK + d * 16), qb = *(const LAS f32x4*)(QK + d * 16 + 4), ka = *(const LAS f32x4*)(QK + d * 16 + 8), kb = *(const LAS f32x4*)(QK + d * 16 + 12);
;         const float dc = DECs[d];
;         o[0] += s0 * qa[0]; o[1] += s0 * qa[1]; o[2] += s0 * qa[2]; o[3] += s0 * qa[3]; o[4] += s0 * qb[0]; o[5] += s0 * qb[1]; o[6] += s0 * qb[2]; o[7] += s0 * qb[3];
;         f32x4 sn = s0 * dc; sn += v[0] * ka[0]; sn += v[1] * ka[1]; sn += v[2] * ka[2]; sn += v[3] * ka[3]; sn += v[4] * kb[0]; sn += v[5] * kb[1]; sn += v[6] * kb[2]; sn += v[7] * kb[3];
;         __builtin_nontemporal_store(sn, (f32x4*)(S1 + (size_t)d * DV + e4 * 4)); }
	s_waitcnt vmcnt(7)
	v_pk_fma_f32 v[36:37], v[190:191], v[38:39], v[66:67] op_sel_hi:[1,0,1]
	v_pk_fma_f32 v[42:43], v[188:189], v[38:39], v[130:131] op_sel_hi:[1,0,1]
	v_pk_fma_f32 v[46:47], v[190:191], v[38:39], v[132:133] op_sel:[0,1,0]
	v_pk_fma_f32 v[48:49], v[188:189], v[38:39], v[60:61] op_sel:[0,1,0]
	v_pk_fma_f32 v[38:39], v[190:191], v[40:41], v[58:59] op_sel_hi:[1,0,1]
	v_pk_fma_f32 v[52:53], v[188:189], v[40:41], v[56:57] op_sel_hi:[1,0,1]
	v_mov_b32_e32 v40, v41
	v_pk_fma_f32 v[44:45], v[190:191], v[40:41], v[136:137] op_sel_hi:[1,0,1]
	v_pk_fma_f32 v[54:55], v[188:189], v[40:41], v[134:135] op_sel_hi:[1,0,1]
	s_waitcnt lgkmcnt(2)
	v_mov_b32_e32 v40, v65
	v_pk_fma_f32 v[50:51], v[190:191], v[62:63], v[110:111] op_sel_hi:[1,0,1]
	v_pk_fma_f32 v[56:57], v[190:191], v[64:65], v[142:143] op_sel_hi:[1,0,1]
	v_pk_fma_f32 v[110:111], v[188:189], v[64:65], v[124:125] op_sel_hi:[1,0,1]
	v_pk_fma_f32 v[64:65], v[190:191], v[40:41], v[122:123] op_sel_hi:[1,0,1]
	v_pk_fma_f32 v[66:67], v[188:189], v[40:41], v[126:127] op_sel_hi:[1,0,1]
	v_mov_b32_e32 v40, v129
	v_pk_fma_f32 v[58:59], v[188:189], v[62:63], v[138:139] op_sel_hi:[1,0,1]
	v_pk_fma_f32 v[60:61], v[190:191], v[62:63], v[140:141] op_sel:[0,1,0]
	v_pk_fma_f32 v[62:63], v[188:189], v[62:63], v[120:121] op_sel:[0,1,0]
	v_pk_mul_f32 v[102:103], v[188:189], v[40:41] op_sel_hi:[1,0]
	v_pk_mul_f32 v[40:41], v[190:191], v[40:41] op_sel_hi:[1,0]
	s_waitcnt lgkmcnt(1)
	v_pk_fma_f32 v[102:103], v[0:1], v[106:107], v[102:103] op_sel_hi:[1,0,1]
	v_pk_fma_f32 v[40:41], v[2:3], v[106:107], v[40:41] op_sel_hi:[1,0,1]
	v_pk_fma_f32 v[102:103], v[4:5], v[106:107], v[102:103] op_sel:[0,1,0]
	v_pk_fma_f32 v[40:41], v[6:7], v[106:107], v[40:41] op_sel:[0,1,0]
	v_pk_fma_f32 v[102:103], v[8:9], v[108:109], v[102:103] op_sel_hi:[1,0,1]
	v_pk_fma_f32 v[40:41], v[10:11], v[108:109], v[40:41] op_sel_hi:[1,0,1]
	v_mov_b32_e32 v104, v109
	v_mov_b32_e32 v105, v191
	v_pk_fma_f32 v[102:103], v[12:13], v[104:105], v[102:103] op_sel_hi:[1,0,1]
	v_pk_fma_f32 v[40:41], v[14:15], v[104:105], v[40:41] op_sel_hi:[1,0,1]
	s_waitcnt lgkmcnt(0)
	v_pk_fma_f32 v[102:103], v[20:21], v[112:113], v[102:103] op_sel_hi:[1,0,1]
	v_pk_fma_f32 v[40:41], v[22:23], v[112:113], v[40:41] op_sel_hi:[1,0,1]
	v_pk_fma_f32 v[102:103], v[24:25], v[112:113], v[102:103] op_sel:[0,1,0]
	v_pk_fma_f32 v[40:41], v[26:27], v[112:113], v[40:41] op_sel:[0,1,0]
	v_pk_fma_f32 v[102:103], v[28:29], v[114:115], v[102:103] op_sel_hi:[1,0,1]
	v_pk_fma_f32 v[40:41], v[30:31], v[114:115], v[40:41] op_sel_hi:[1,0,1]
	v_mov_b32_e32 v104, v115
	v_pk_fma_f32 v[102:103], v[32:33], v[104:105], v[102:103] op_sel_hi:[1,0,1]
	v_pk_fma_f32 v[104:105], v[34:35], v[104:105], v[40:41] op_sel_hi:[1,0,1]
	v_lshl_add_u64 v[40:41], v[78:79], 0, v[18:19]
	global_store_dwordx4 v[40:41], v[102:105], off nt
	v_lshl_add_u64 v[40:41], v[76:77], 0, v[18:19]
	s_nop 0
	ds_read_b128 v[104:107], v118 offset:6144
	ds_read_b128 v[124:127], v118 offset:6160
	ds_read_b128 v[128:131], v118 offset:6176
	ds_read_b128 v[132:135], v118 offset:6192
	ds_read2_b32 v[102:103], v16 offset0:96 offset1:112
	v_add_u32_e32 v16, 0x200, v16
	v_lshl_add_u64 v[76:77], v[76:77], 0, s[44:45]
	v_lshl_add_u64 v[78:79], v[78:79], 0, s[44:45]
	s_waitcnt lgkmcnt(4)
	s_waitcnt vmcnt(7)
	v_pk_fma_f32 v[40:41], v[196:197], v[104:105], v[36:37] op_sel_hi:[1,0,1]
	v_pk_fma_f32 v[42:43], v[194:195], v[104:105], v[42:43] op_sel_hi:[1,0,1]
	v_pk_fma_f32 v[46:47], v[196:197], v[104:105], v[46:47] op_sel:[0,1,0]
	v_pk_fma_f32 v[48:49], v[194:195], v[104:105], v[48:49] op_sel:[0,1,0]
	v_mov_b32_e32 v104, v107
	s_waitcnt lgkmcnt(3)
	v_pk_fma_f32 v[114:115], v[196:197], v[126:127], v[56:57] op_sel_hi:[1,0,1]
	v_mov_b32_e32 v56, v127
	v_pk_fma_f32 v[36:37], v[194:195], v[106:107], v[52:53] op_sel_hi:[1,0,1]
	v_pk_fma_f32 v[52:53], v[196:197], v[106:107], v[38:39] op_sel_hi:[1,0,1]
	v_pk_fma_f32 v[38:39], v[194:195], v[104:105], v[54:55] op_sel_hi:[1,0,1]
	v_pk_fma_f32 v[54:55], v[196:197], v[104:105], v[44:45] op_sel_hi:[1,0,1]
	v_pk_fma_f32 v[104:105], v[194:195], v[124:125], v[58:59] op_sel_hi:[1,0,1]
	v_pk_fma_f32 v[44:45], v[194:195], v[126:127], v[110:111] op_sel_hi:[1,0,1]
	v_pk_fma_f32 v[110:111], v[196:197], v[56:57], v[64:65] op_sel_hi:[1,0,1]
	v_pk_fma_f32 v[112:113], v[194:195], v[56:57], v[66:67] op_sel_hi:[1,0,1]
	s_waitcnt lgkmcnt(0)
; #define LAS __attribute__((address_space(3)))
; template <int TY> __device__ __forceinline__ void sample_item(const Params& p, ldsp lds, int item) {
;     ...
; #pragma unroll 8
;     for (int d = dg; d < DK; d += NG) { const f32x4 s0 = __builtin_nontemporal_load((const f32x4*)(S0 + (size_t)d * DV + e4 * 4));
;         const f32x4 qa = *(const LAS f32x4*)(QK + d * 16), qb = *(const LAS f32x4*)(QK + d * 16 + 4), ka = *(const LAS f32x4*)(QK + d * 16 + 8), kb = *(const LAS f32x4*)(QK + d * 16 + 12);
;         const float dc = DECs[d];
;         o[0] += s0 * qa[0]; o[1] += s0 * qa[1]; o[2] += s0 * qa[2]; o[3] += s0 * qa[3]; o[4] += s0 * qb[0]; o[5] += s0 * qb[1]; o[6] += s0 * qb[2]; o[7] += s0 * qb[3];
;         f32x4 sn = s0 * dc; sn += v[0] * ka[0]; sn += v[1] * ka[1]; sn += v[2] * ka[2]; sn += v[3] * ka[3]; sn += v[4] * kb[0]; sn += v[5] * kb[1]; sn += v[6] * kb[2]; sn += v[7] * kb[3];
;         __builtin_nontemporal_store(sn, (f32x4*)(S1 + (size_t)d * DV + e4 * 4)); }
	v_pk_mul_f32 v[56:57], v[194:195], v[102:103] op_sel_hi:[1,0]
	v_pk_mul_f32 v[58:59], v[196:197], v[102:103] op_sel_hi:[1,0]
	v_pk_fma_f32 v[56:57], v[0:1], v[128:129], v[56:57] op_sel_hi:[1,0,1]
	v_pk_fma_f32 v[58:59], v[2:3], v[128:129], v[58:59] op_sel_hi:[1,0,1]
	v_pk_fma_f32 v[56:57], v[4:5], v[128:129], v[56:57] op_sel:[0,1,0]
	v_pk_fma_f32 v[58:59], v[6:7], v[128:129], v[58:59] op_sel:[0,1,0]
	v_pk_fma_f32 v[106:107], v[196:197], v[124:125], v[60:61] op_sel:[0,1,0]
	v_pk_fma_f32 v[58:59], v[10:11], v[130:131], v[58:59] op_sel_hi:[1,0,1]
	v_pk_fma_f32 v[56:57], v[8:9], v[130:131], v[56:57] op_sel_hi:[1,0,1]
	v_mov_b32_e32 v60, v131
	v_pk_fma_f32 v[56:57], v[12:13], v[60:61], v[56:57] op_sel_hi:[1,0,1]
	v_pk_fma_f32 v[58:59], v[14:15], v[60:61], v[58:59] op_sel_hi:[1,0,1]
	v_pk_fma_f32 v[56:57], v[20:21], v[132:133], v[56:57] op_sel_hi:[1,0,1]
	v_pk_fma_f32 v[58:59], v[22:23], v[132:133], v[58:59] op_sel_hi:[1,0,1]
	v_pk_fma_f32 v[56:57], v[24:25], v[132:133], v[56:57] op_sel:[0,1,0]
	v_pk_fma_f32 v[58:59], v[26:27], v[132:133], v[58:59] op_sel:[0,1,0]
	v_pk_fma_f32 v[56:57], v[28:29], v[134:135], v[56:57] op_sel_hi:[1,0,1]
	v_pk_fma_f32 v[58:59], v[30:31], v[134:135], v[58:59] op_sel_hi:[1,0,1]
	v_mov_b32_e32 v60, v135
	v_pk_fma_f32 v[56:57], v[32:33], v[60:61], v[56:57] op_sel_hi:[1,0,1]
	v_pk_fma_f32 v[58:59], v[34:35], v[60:61], v[58:59] op_sel_hi:[1,0,1]
	v_lshl_add_u64 v[60:61], v[74:75], 0, v[18:19]
	global_store_dwordx4 v[60:61], v[56:59], off nt
	v_pk_fma_f32 v[50:51], v[196:197], v[124:125], v[50:51] op_sel_hi:[1,0,1]
	v_pk_fma_f32 v[108:109], v[194:195], v[124:125], v[62:63] op_sel:[0,1,0]
	v_lshl_add_u64 v[56:57], v[72:73], 0, v[18:19]
	s_nop 0
	ds_read_b128 v[124:127], v118 offset:7168
	ds_read_b128 v[128:131], v118 offset:7184
	ds_read_b128 v[132:135], v118 offset:7200
	ds_read_b128 v[136:139], v118 offset:7216
	v_mov_b32_e32 v102, v103
	v_add_u32_e32 v118, 0x2000, v118
	v_lshl_add_u64 v[72:73], v[72:73], 0, s[44:45]
	v_lshl_add_u64 v[74:75], v[74:75], 0, s[44:45]
	s_waitcnt lgkmcnt(3)
	s_waitcnt vmcnt(7)
	v_pk_fma_f32 v[60:61], v[206:207], v[124:125], v[48:49] op_sel:[0,1,0]
	s_waitcnt lgkmcnt(2)
	v_pk_fma_f32 v[48:49], v[206:207], v[128:129], v[104:105] op_sel_hi:[1,0,1]
	v_pk_mul_f32 v[104:105], v[206:207], v[102:103] op_sel_hi:[1,0]
	v_pk_mul_f32 v[102:103], v[208:209], v[102:103] op_sel_hi:[1,0]
	s_waitcnt lgkmcnt(1)
	v_pk_fma_f32 v[104:105], v[0:1], v[132:133], v[104:105] op_sel_hi:[1,0,1]
	v_pk_fma_f32 v[102:103], v[2:3], v[132:133], v[102:103] op_sel_hi:[1,0,1]
	v_pk_fma_f32 v[104:105], v[4:5], v[132:133], v[104:105] op_sel:[0,1,0]
	v_pk_fma_f32 v[102:103], v[6:7], v[132:133], v[102:103] op_sel:[0,1,0]
	v_pk_fma_f32 v[64:65], v[206:207], v[124:125], v[42:43] op_sel_hi:[1,0,1]
	v_pk_fma_f32 v[42:43], v[208:209], v[128:129], v[106:107] op_sel:[0,1,0]
	v_pk_fma_f32 v[102:103], v[10:11], v[134:135], v[102:103] op_sel_hi:[1,0,1]
	v_pk_fma_f32 v[104:105], v[8:9], v[134:135], v[104:105] op_sel_hi:[1,0,1]
	v_mov_b32_e32 v106, v135
	v_pk_fma_f32 v[104:105], v[12:13], v[106:107], v[104:105] op_sel_hi:[1,0,1]
	v_pk_fma_f32 v[102:103], v[14:15], v[106:107], v[102:103] op_sel_hi:[1,0,1]
	s_waitcnt lgkmcnt(0)
	v_pk_fma_f32 v[104:105], v[20:21], v[136:137], v[104:105] op_sel_hi:[1,0,1]
	v_pk_fma_f32 v[102:103], v[22:23], v[136:137], v[102:103] op_sel_hi:[1,0,1]
	v_pk_fma_f32 v[56:57], v[206:207], v[126:127], v[36:37] op_sel_hi:[1,0,1]
	v_mov_b32_e32 v36, v127
	v_pk_fma_f32 v[104:105], v[24:25], v[136:137], v[104:105] op_sel:[0,1,0]
	v_pk_fma_f32 v[102:103], v[26:27], v[136:137], v[102:103] op_sel:[0,1,0]
	v_pk_fma_f32 v[58:59], v[208:209], v[126:127], v[52:53] op_sel_hi:[1,0,1]
	v_pk_fma_f32 v[54:55], v[208:209], v[36:37], v[54:55] op_sel_hi:[1,0,1]
	v_pk_fma_f32 v[52:53], v[206:207], v[36:37], v[38:39] op_sel_hi:[1,0,1]
	v_pk_fma_f32 v[36:37], v[206:207], v[130:131], v[44:45] op_sel_hi:[1,0,1]
	v_mov_b32_e32 v44, v131
	v_pk_fma_f32 v[106:107], v[30:31], v[138:139], v[102:103] op_sel_hi:[1,0,1]
	v_pk_fma_f32 v[102:103], v[28:29], v[138:139], v[104:105] op_sel_hi:[1,0,1]
	v_mov_b32_e32 v104, v139
	v_pk_fma_f32 v[66:67], v[208:209], v[124:125], v[40:41] op_sel_hi:[1,0,1]
	v_pk_fma_f32 v[62:63], v[208:209], v[124:125], v[46:47] op_sel:[0,1,0]
	v_pk_fma_f32 v[50:51], v[208:209], v[128:129], v[50:51] op_sel_hi:[1,0,1]
	v_pk_fma_f32 v[40:41], v[206:207], v[128:129], v[108:109] op_sel:[0,1,0]
	v_pk_fma_f32 v[38:39], v[208:209], v[130:131], v[114:115] op_sel_hi:[1,0,1]
	v_pk_fma_f32 v[46:47], v[208:209], v[44:45], v[110:111] op_sel_hi:[1,0,1]
	v_pk_fma_f32 v[44:45], v[206:207], v[44:45], v[112:113] op_sel_hi:[1,0,1]
	v_pk_fma_f32 v[102:103], v[32:33], v[104:105], v[102:103] op_sel_hi:[1,0,1]
	v_pk_fma_f32 v[104:105], v[34:35], v[104:105], v[106:107] op_sel_hi:[1,0,1]
	v_lshl_add_u64 v[106:107], v[70:71], 0, v[18:19]
	v_lshl_add_u64 v[70:71], v[70:71], 0, s[44:45]
	global_store_dwordx4 v[106:107], v[102:105], off nt
	s_andn2_b64 exec, exec, s[10:11]
	s_cbranch_execnz .LBB0_1039
	s_or_b64 exec, exec, s[10:11]
